# in_proj phase: half of the workgroups run their ctx projection item before their GEMM units so epilogue store bursts of the two halves interleave
# baseline (speedup 1.0000x reference)
; #define LAS __attribute__((address_space(3)))
;     __device__ bool next(int i, Unit& u) const { const int L = i * G + vc; if (L >= n) return false; u.g = L / (npm * npn); u.pm = (L / npn) % npm; u.pn = L % npn; return true; }
; #define SUB(i, ...) do { if (PROBE_PH == phk && PROBE_SUB == (i)) { __syncthreads(); tp0 = __builtin_amdgcn_s_memrealtime(); } __VA_ARGS__ if (PROBE_PH == phk && PROBE_SUB == (i)) { asm volatile("s_waitcnt vmcnt(0)" ::: "memory"); __syncthreads(); tp1 = __builtin_amdgcn_s_memrealtime(); } } while (0)
;     __device__ bool next(int i, Unit& u) const {
;         const long L = (long)i * G + c; if (L >= nwg) return false;
;         int wgid = (int)L; { const int q = nwg / NXCD, r = nwg % NXCD, xcd = wgid % NXCD, off = wgid / NXCD; wgid = (xcd < r ? xcd * (q + 1) : r * (q + 1) + (xcd - r) * q) + off; }
;         const int nig = wgm * nN, gid = wgid / nig, fm = gid * wgm, gsz = (nM - fm) < wgm ? (nM - fm) : wgm;
;         u.pm = fm + ((wgid % nig) % gsz); u.pn = (wgid % nig) / gsz; u.g = 0; return true;
; __global__ void __launch_bounds__(NTHREADS, 2) mk_fwd(Args a) {
;     ...
;     PHASE(2,
;         pg8::DenseOrder S; S.init(M_LAT / 256, 12, G, bx, WGM_IN);
;         EpiInProj E{(f16*)(a.ws + WS_UPOOL), (f16*)(a.ws + WS_X), (f16*)(a.ws + WS_ZS)};
;         SUB(0, pg8::gemm_phase<CfgDense2048, EpiInProj, pg8::DenseOrder, true, true>(lds, (const char*)(a.ws + WS_H), (const char*)(a.ws + WS_WIN), S, E); );
;         for (int it = bx; it < 256; it += G) ctx_item((LAS float*)lds, it, (const f16*)(a.ws + WS_H) + (size_t)M_LAT * D, (const f16*)(a.ws + WS_WIN) + (size_t)PW * D, (f16*)(a.ws + WS_X));
.LBB0_284:
	s_mov_b32 s98, 0
	s_cmp_lt_i32 s78, 3
	s_cselect_b64 s[0:1], -1, 0
	s_and_b64 s[6:7], s[0:1], s[2:3]
	s_andn2_b64 vcc, exec, s[6:7]
	s_cbranch_vccnz .LBB0_436
	s_bitcmp1_b32 s16, 3
	s_cbranch_scc0 .Lp2_gemm
	s_mov_b32 s98, 1
	v_lshrrev_b32_e32 v1, 3, v0
	v_and_b32_e32 v130, 15, v0
	v_lshrrev_b32_e32 v131, 2, v0
	s_add_u32 s8, s50, 0xc300000
	s_addc_u32 s9, s51, 0
	s_branch .LBB0_431
.Lp2_gemm:
	s_cmpk_lt_i32 s16, 0x300
	s_cselect_b64 s[2:3], -1, 0
	s_cmpk_gt_i32 s16, 0x2ff
	v_readfirstlane_b32 s18, v0
	s_cbranch_scc1 .LBB0_287
	s_ashr_i32 s0, s16, 31
	s_lshr_b32 s0, s0, 29
	s_add_i32 s0, s16, s0
	s_ashr_i32 s1, s0, 3
	s_and_b32 s0, s0, -8
	s_sub_i32 s0, s16, s0
	s_cmp_lt_i32 s0, 0
	s_movk_i32 s4, 0x61
	s_cselect_b32 s4, s4, 0x60
	s_mul_i32 s0, s0, s4
	s_add_i32 s0, s0, s1
	s_mul_hi_i32 s1, s0, 0x2aaaaaab
	s_lshr_b32 s4, s1, 31
	s_ashr_i32 s1, s1, 4
	s_add_i32 s1, s1, s4
	s_lshl_b32 s4, s1, 3
	s_mulk_i32 s1, 0x60
	s_sub_i32 s0, s0, s1
	s_bfe_i32 s1, s0, 0x80000
	s_bfe_u32 s1, s1, 0x3000c
	s_add_i32 s1, s0, s1
	s_bfe_i32 s5, s1, 0x80000
	s_and_b32 s1, s1, 0xf8
	s_sub_i32 s0, s0, s1
	s_sext_i32_i16 s5, s5
	s_sext_i32_i8 s0, s0
	s_add_i32 s4, s4, s0
	s_ashr_i32 s36, s5, 3

; #define LAS __attribute__((address_space(3)))
; __device__ __forceinline__ void ctx_item(LAS float* L, int item, const f16* hc, const f16* Wssm, f16* X) {
;     const int tid = threadIdx.x, wave = tid >> 6, lane = tid & 63, rb = item >> 4, cb = item & 15, k0 = wave * 256 + 8 * (lane >> 5);
;     const f16* ap = hc + (size_t)(rb * 32 + (lane & 31)) * D + k0;
;     const f16* bp0 = Wssm + (size_t)(cb * 64 + (lane & 31)) * D + k0; const f16* bp1 = bp0 + (size_t)32 * D;
; __global__ void __launch_bounds__(NTHREADS, 2) mk_fwd(Args a) {
;     ...
;         for (int it = bx; it < 256; it += G) ctx_item((LAS float*)lds, it, (const f16*)(a.ws + WS_H) + (size_t)M_LAT * D, (const f16*)(a.ws + WS_WIN) + (size_t)PW * D, (f16*)(a.ws + WS_X));
.LBB0_431:
	s_cmp_eq_u32 s98, 2
	s_cbranch_scc1 .LBB0_436
	s_cmpk_gt_i32 s16, 0xff
	s_cbranch_scc1 .LBB0_436
	v_lshrrev_b32_e32 v4, 6, v0
	v_lshlrev_b32_e32 v55, 8, v4
	v_and_or_b32 v2, v131, 8, v55
	v_lshlrev_b32_e32 v34, 1, v2
	v_mov_b32_e32 v35, 0
	v_lshl_add_u64 v[2:3], s[50:51], 0, v[34:35]
	s_mov_b64 s[0:1], 0x800000
	v_lshl_add_u64 v[36:37], v[2:3], 0, s[0:1]
	s_mov_b64 s[0:1], 0xa100000
	v_lshl_add_u64 v[38:39], v[2:3], 0, s[0:1]
	v_lshlrev_b32_e32 v3, 13, v4
	v_or_b32_e32 v4, 0x200, v0
	v_lshlrev_b32_e32 v6, 2, v4
	v_and_b32_e32 v7, 0xf00, v6
	v_or_b32_e32 v6, 0x600, v0
	v_lshrrev_b32_e32 v2, 5, v0
	v_lshrrev_b32_e32 v4, 5, v4
	v_lshlrev_b32_e32 v8, 2, v6
	v_lshrrev_b32_e32 v6, 5, v6
	v_and_b32_e32 v1, 4, v1
	v_bfe_u32 v5, v0, 6, 2
	v_and_b32_e32 v2, 8, v2
	v_and_b32_e32 v4, 24, v4
	v_and_b32_e32 v6, 24, v6
	v_lshl_add_u32 v54, v212, 2, 0
	v_or3_b32 v2, v5, v2, v1
	v_or3_b32 v4, v5, v4, v1
	v_or3_b32 v1, v5, v6, v1
	v_lshlrev_b32_e32 v2, 4, v2
	v_lshlrev_b32_e32 v4, 4, v4
	v_and_b32_e32 v8, 0xf00, v8
	v_add_u32_e32 v9, 0x1000, v54
	v_lshlrev_b32_e32 v6, 4, v1
	s_mov_b32 s3, 0
	v_and_b32_e32 v56, 31, v0
	s_mov_b64 s[4:5], 0x20000
	v_add_u32_e32 v1, v54, v3
	v_lshlrev_b32_e32 v40, 1, v2
	v_lshlrev_b32_e32 v42, 1, v130
	v_add_u32_e32 v57, v54, v7
	v_lshlrev_b32_e32 v44, 1, v4
	s_mov_b32 s0, 0x18c000
	v_add_u32_e32 v58, v9, v8
	v_lshlrev_b32_e32 v46, 1, v6
	s_mov_b32 s1, s16

; #define LAS __attribute__((address_space(3)))
; #define SUB(i, ...) do { if (PROBE_PH == phk && PROBE_SUB == (i)) { __syncthreads(); tp0 = __builtin_amdgcn_s_memrealtime(); } __VA_ARGS__ if (PROBE_PH == phk && PROBE_SUB == (i)) { asm volatile("s_waitcnt vmcnt(0)" ::: "memory"); __syncthreads(); tp1 = __builtin_amdgcn_s_memrealtime(); } } while (0)
; __global__ void __launch_bounds__(NTHREADS, 2) mk_fwd(Args a) {
;     ...
;     PHASE(2,
;         pg8::DenseOrder S; S.init(M_LAT / 256, 12, G, bx, WGM_IN);
;         EpiInProj E{(f16*)(a.ws + WS_UPOOL), (f16*)(a.ws + WS_X), (f16*)(a.ws + WS_ZS)};
;         SUB(0, pg8::gemm_phase<CfgDense2048, EpiInProj, pg8::DenseOrder, true, true>(lds, (const char*)(a.ws + WS_H), (const char*)(a.ws + WS_WIN), S, E); );
;         for (int it = bx; it < 256; it += G) ctx_item((LAS float*)lds, it, (const f16*)(a.ws + WS_H) + (size_t)M_LAT * D, (const f16*)(a.ws + WS_WIN) + (size_t)PW * D, (f16*)(a.ws + WS_X));
;     );
.LBB0_436:
	s_cmp_lg_u32 s98, 1
	s_cbranch_scc1 .Lp2_seam
	s_mov_b32 s98, 2
	s_branch .Lp2_gemm
